# rotK + non-temporal hint on P4's once-read xp row loads and once-written out stores
# speedup vs baseline: 1.0051x; 1.0051x over previous
; __device__ __forceinline__ float bf_lo(unsigned w) { return __uint_as_float(w << 16); }
; __device__ __forceinline__ float bf_hi(unsigned w) { return __uint_as_float(w & 0xffff0000u); }
; __device__ __forceinline__ void phase4(const Params& P, int lane, int wave) {
;     ...
;     for (int j = 0; j < 4; ++j) g4[j] = *(const f32x4*)(P.fgain + 4 * lane + 256 * j);
;     f32x4 v[4]; u32x2 mv[4];
;     int m = gw;
;     if (m < MT) {
;         const float* xrow = (m < MP) ? P.xp + (size_t)m * 1024 : P.xs + (size_t)(m - MP) * 1024;
; #pragma unroll
;         for (int j = 0; j < 4; ++j) { v[j] = *(const f32x4*)(xrow + 4 * lane + 256 * j); mv[j] = *(const u32x2*)(mo + (size_t)m * 1024 + 4 * lane + 256 * j); }
;     }
;     for (; m < MT; m += NGW) {
;         f32x4 r[4]; float ss = 0.f;
; #pragma unroll
;         for (int j = 0; j < 4; ++j) {
;             r[j][0] = v[j][0] + bf_lo(mv[j].x); r[j][1] = v[j][1] + bf_hi(mv[j].x); r[j][2] = v[j][2] + bf_lo(mv[j].y); r[j][3] = v[j][3] + bf_hi(mv[j].y);
;             ss += (r[j][0] * r[j][0] + r[j][1] * r[j][1]) + (r[j][2] * r[j][2] + r[j][3] * r[j][3]);
.LBB0_793:
	s_or_b64 exec, exec, s[0:1]
	v_readlane_b32 s0, v241, 12
	v_readlane_b32 s1, v241, 13
	s_andn2_b64 vcc, exec, s[0:1]
	s_waitcnt lgkmcnt(0)
	s_barrier
	s_cbranch_vccnz .LBB0_806
	v_mbcnt_hi_u32_b32 v82, -1, v179
	v_lshlrev_b32_e32 v80, 4, v82
	v_lshlrev_b32_e32 v81, 3, v82
	global_load_dwordx4 v[0:3], v80, s[88:89]
	global_load_dwordx4 v[4:7], v80, s[88:89] offset:1024
	global_load_dwordx4 v[8:11], v80, s[88:89] offset:2048
	global_load_dwordx4 v[12:15], v80, s[88:89] offset:3072
	v_xor_b32_e32 v72, 1, v82
	v_lshlrev_b32_e32 v72, 2, v72
	v_xor_b32_e32 v73, 2, v82
	v_lshlrev_b32_e32 v73, 2, v73
	v_xor_b32_e32 v74, 4, v82
	v_lshlrev_b32_e32 v74, 2, v74
	v_xor_b32_e32 v75, 8, v82
	v_lshlrev_b32_e32 v75, 2, v75
	v_xor_b32_e32 v76, 16, v82
	v_lshlrev_b32_e32 v76, 2, v76
	v_xor_b32_e32 v77, 32, v82
	v_lshlrev_b32_e32 v77, 2, v77
	v_mov_b32_e32 v70, 0x358637bd
	v_mov_b32_e32 v71, 0x260
	s_mov_b32 s2, 0xf800000
	v_readlane_b32 s8, v241, 10
	s_mov_b32 s11, s8
	s_mov_b32 s16, s11
	s_lshl_b32 s17, s16, 11
	s_add_u32 s14, s4, s17
	s_addc_u32 s15, s5, 0
	s_add_i32 s18, s16, 0xffff0000
	s_cmp_lt_u32 s16, 0x10000
	s_cselect_b32 s18, s16, s18
	s_cselect_b32 s12, s68, s70
	s_cselect_b32 s13, s69, s71
	s_lshr_b32 s19, s18, 20
	s_lshl_b32 s18, s18, 12
	s_add_u32 s12, s12, s18
	s_addc_u32 s13, s13, s19
	global_load_dwordx4 v[16:19], v80, s[12:13] nt
	global_load_dwordx4 v[20:23], v80, s[12:13] offset:1024 nt
	global_load_dwordx4 v[24:27], v80, s[12:13] offset:2048 nt
	global_load_dwordx4 v[28:31], v80, s[12:13] offset:3072 nt
	global_load_dwordx2 v[32:33], v81, s[14:15]
	global_load_dwordx2 v[34:35], v81, s[14:15] offset:512
	global_load_dwordx2 v[36:37], v81, s[14:15] offset:1024
	global_load_dwordx2 v[38:39], v81, s[14:15] offset:1536
	s_add_i32 s20, s11, s84
	s_cmp_lt_u32 s20, 0x10100
	s_cselect_b32 s20, s20, s11
	s_mov_b32 s16, s20
	s_lshl_b32 s17, s16, 11
	s_add_u32 s14, s4, s17
	s_addc_u32 s15, s5, 0
	s_add_i32 s18, s16, 0xffff0000
	s_cmp_lt_u32 s16, 0x10000
	s_cselect_b32 s18, s16, s18
	s_cselect_b32 s12, s68, s70
	s_cselect_b32 s13, s69, s71
	s_lshr_b32 s19, s18, 20
	s_lshl_b32 s18, s18, 12
	s_add_u32 s12, s12, s18
	s_addc_u32 s13, s13, s19
	global_load_dwordx4 v[40:43], v80, s[12:13] nt
	global_load_dwordx4 v[44:47], v80, s[12:13] offset:1024 nt
	global_load_dwordx4 v[48:51], v80, s[12:13] offset:2048 nt
	global_load_dwordx4 v[52:55], v80, s[12:13] offset:3072 nt
	global_load_dwordx2 v[56:57], v81, s[14:15]
	global_load_dwordx2 v[58:59], v81, s[14:15] offset:512
	global_load_dwordx2 v[60:61], v81, s[14:15] offset:1024
	global_load_dwordx2 v[62:63], v81, s[14:15] offset:1536
.Lp4_loop:
	s_lshl_b32 s20, s84, 1
	s_add_i32 s20, s11, s20
	s_cmp_lt_u32 s20, 0x10100
	s_cselect_b32 s20, s20, s11
	s_mov_b32 s16, s20
	s_lshl_b32 s17, s16, 11
	s_add_u32 s14, s4, s17
	s_addc_u32 s15, s5, 0
	s_add_i32 s18, s16, 0xffff0000
	s_cmp_lt_u32 s16, 0x10000
	s_cselect_b32 s18, s16, s18
	s_cselect_b32 s12, s68, s70
	s_cselect_b32 s13, s69, s71
	s_lshr_b32 s19, s18, 20
	s_lshl_b32 s18, s18, 12
	s_add_u32 s12, s12, s18
	s_addc_u32 s13, s13, s19
	global_load_dwordx4 v[88:91], v80, s[12:13] nt
	global_load_dwordx4 v[92:95], v80, s[12:13] offset:1024 nt
	global_load_dwordx4 v[96:99], v80, s[12:13] offset:2048 nt
	global_load_dwordx4 v[100:103], v80, s[12:13] offset:3072 nt
	global_load_dwordx2 v[104:105], v81, s[14:15]
	global_load_dwordx2 v[106:107], v81, s[14:15] offset:512
	global_load_dwordx2 v[108:109], v81, s[14:15] offset:1024
	global_load_dwordx2 v[110:111], v81, s[14:15] offset:1536
	s_lshr_b32 s19, s11, 20
	s_lshl_b32 s18, s11, 12
	s_add_u32 s0, s90, s18
	s_addc_u32 s1, s91, s19
	s_waitcnt vmcnt(16)
	v_lshlrev_b32_e32 v64, 16, v32
	v_and_b32_e32 v65, 0xffff0000, v32
	v_add_f32_e32 v16, v16, v64
	v_add_f32_e32 v17, v17, v65
	v_lshlrev_b32_e32 v64, 16, v33
	v_and_b32_e32 v65, 0xffff0000, v33
	v_add_f32_e32 v18, v18, v64
	v_add_f32_e32 v19, v19, v65
	v_lshlrev_b32_e32 v64, 16, v34
	v_and_b32_e32 v65, 0xffff0000, v34
	v_add_f32_e32 v20, v20, v64
	v_add_f32_e32 v21, v21, v65
	v_lshlrev_b32_e32 v64, 16, v35
	v_and_b32_e32 v65, 0xffff0000, v35
	v_add_f32_e32 v22, v22, v64
	v_add_f32_e32 v23, v23, v65
	v_lshlrev_b32_e32 v64, 16, v36
	v_and_b32_e32 v65, 0xffff0000, v36
	v_add_f32_e32 v24, v24, v64
	v_add_f32_e32 v25, v25, v65
	v_lshlrev_b32_e32 v64, 16, v37
	v_and_b32_e32 v65, 0xffff0000, v37
	v_add_f32_e32 v26, v26, v64
	v_add_f32_e32 v27, v27, v65
	v_lshlrev_b32_e32 v64, 16, v38
	v_and_b32_e32 v65, 0xffff0000, v38
	v_add_f32_e32 v28, v28, v64
	v_add_f32_e32 v29, v29, v65
	v_lshlrev_b32_e32 v64, 16, v39
	v_and_b32_e32 v65, 0xffff0000, v39
	v_add_f32_e32 v30, v30, v64
	v_add_f32_e32 v31, v31, v65
	v_mul_f32_e32 v64, v16, v16
	v_mul_f32_e32 v65, v17, v17
	v_mul_f32_e32 v66, v18, v18
	v_mul_f32_e32 v67, v19, v19
	v_add_f32_e32 v64, v64, v65
	v_add_f32_e32 v66, v66, v67
	v_add_f32_e32 v68, v64, v66
	v_mul_f32_e32 v64, v20, v20
	v_mul_f32_e32 v65, v21, v21
	v_mul_f32_e32 v66, v22, v22
	v_mul_f32_e32 v67, v23, v23
	v_add_f32_e32 v64, v64, v65
	v_add_f32_e32 v66, v66, v67
	v_add_f32_e32 v64, v64, v66
	v_add_f32_e32 v68, v68, v64
	v_mul_f32_e32 v64, v24, v24
	v_mul_f32_e32 v65, v25, v25
	v_mul_f32_e32 v66, v26, v26
	v_mul_f32_e32 v67, v27, v27
	v_add_f32_e32 v64, v64, v65
	v_add_f32_e32 v66, v66, v67
	v_add_f32_e32 v64, v64, v66
	v_add_f32_e32 v68, v68, v64
	v_mul_f32_e32 v64, v28, v28
	v_mul_f32_e32 v65, v29, v29
	v_mul_f32_e32 v66, v30, v30
	v_mul_f32_e32 v67, v31, v31
	v_add_f32_e32 v64, v64, v65
	v_add_f32_e32 v66, v66, v67
	v_add_f32_e32 v64, v64, v66
	v_add_f32_e32 v68, v68, v64
	ds_bpermute_b32 v69, v72, v68
	s_waitcnt lgkmcnt(0)
; __device__ __forceinline__ float bf_lo(unsigned w) { return __uint_as_float(w << 16); }
; __device__ __forceinline__ float bf_hi(unsigned w) { return __uint_as_float(w & 0xffff0000u); }
; __device__ __forceinline__ void phase4(const Params& P, int lane, int wave) {
;     ...
;         for (int j = 0; j < 4; ++j) {
;             r[j][0] = v[j][0] + bf_lo(mv[j].x); r[j][1] = v[j][1] + bf_hi(mv[j].x); r[j][2] = v[j][2] + bf_lo(mv[j].y); r[j][3] = v[j][3] + bf_hi(mv[j].y);
;             ss += (r[j][0] * r[j][0] + r[j][1] * r[j][1]) + (r[j][2] * r[j][2] + r[j][3] * r[j][3]);
;         }
;         const int mn = m + NGW;
;         if (mn < MT) {
;             const float* xrow = (mn < MP) ? P.xp + (size_t)mn * 1024 : P.xs + (size_t)(mn - MP) * 1024;
; #pragma unroll
;             for (int j = 0; j < 4; ++j) { v[j] = *(const f32x4*)(xrow + 4 * lane + 256 * j); mv[j] = *(const u32x2*)(mo + (size_t)mn * 1024 + 4 * lane + 256 * j); }
;         }
;         ss = wave_sum(ss);
;         const float rstd = 1.0f / sqrtf(ss * (1.0f / 1024.0f) + RMS_EPS);
;         float* row = P.out + (size_t)m * 1024;
; #pragma unroll
;         for (int j = 0; j < 4; ++j) *(f32x4*)(row + 4 * lane + 256 * j) = r[j] * rstd * g4[j];
	v_add_f32_e32 v68, v68, v69
	ds_bpermute_b32 v69, v73, v68
	s_waitcnt lgkmcnt(0)
	v_add_f32_e32 v68, v68, v69
	ds_bpermute_b32 v69, v74, v68
	s_waitcnt lgkmcnt(0)
	v_add_f32_e32 v68, v68, v69
	ds_bpermute_b32 v69, v75, v68
	s_waitcnt lgkmcnt(0)
	v_add_f32_e32 v68, v68, v69
	ds_bpermute_b32 v69, v76, v68
	s_waitcnt lgkmcnt(0)
	v_add_f32_e32 v68, v68, v69
	ds_bpermute_b32 v69, v77, v68
	s_waitcnt lgkmcnt(0)
	v_add_f32_e32 v68, v68, v69
	v_fmamk_f32 v68, v68, 0x3a800000, v70
	v_mul_f32_e32 v69, 0x4f800000, v68
	v_cmp_gt_f32_e32 vcc, s2, v68
	s_nop 1
	v_cndmask_b32_e32 v68, v68, v69, vcc
	v_sqrt_f32_e32 v69, v68
	s_nop 0
	v_add_u32_e32 v64, -1, v69
	v_fma_f32 v65, -v64, v69, v68
	v_cmp_ge_f32_e64 s[6:7], 0, v65
	v_add_u32_e32 v65, 1, v69
	s_nop 0
	v_cndmask_b32_e64 v64, v69, v64, s[6:7]
	v_fma_f32 v69, -v65, v69, v68
	v_cmp_lt_f32_e64 s[6:7], 0, v69
	s_nop 1
	v_cndmask_b32_e64 v69, v64, v65, s[6:7]
	v_mul_f32_e32 v64, 0x37800000, v69
	v_cndmask_b32_e32 v69, v69, v64, vcc
	v_cmp_class_f32_e32 vcc, v68, v71
	s_nop 1
	v_cndmask_b32_e32 v68, v69, v68, vcc
	v_div_scale_f32 v69, s[6:7], v68, v68, 1.0
	v_rcp_f32_e32 v64, v69
	s_nop 0
	v_fma_f32 v65, -v69, v64, 1.0
	v_fmac_f32_e32 v64, v65, v64
	v_div_scale_f32 v65, vcc, 1.0, v68, 1.0
	v_mul_f32_e32 v66, v65, v64
	v_fma_f32 v67, -v69, v66, v65
	v_fmac_f32_e32 v66, v67, v64
	v_fma_f32 v69, -v69, v66, v65
	v_div_fmas_f32 v69, v69, v64, v66
	v_div_fixup_f32 v68, v69, v68, 1.0
	v_mul_f32_e32 v16, v16, v68
	v_mul_f32_e32 v17, v17, v68
	v_mul_f32_e32 v18, v18, v68
	v_mul_f32_e32 v19, v19, v68
	v_mul_f32_e32 v16, v0, v16
	v_mul_f32_e32 v17, v1, v17
	v_mul_f32_e32 v18, v2, v18
	v_mul_f32_e32 v19, v3, v19
	global_store_dwordx4 v80, v[16:19], s[0:1] nt
	v_mul_f32_e32 v20, v20, v68
	v_mul_f32_e32 v21, v21, v68
	v_mul_f32_e32 v22, v22, v68
	v_mul_f32_e32 v23, v23, v68
	v_mul_f32_e32 v20, v4, v20
	v_mul_f32_e32 v21, v5, v21
	v_mul_f32_e32 v22, v6, v22
	v_mul_f32_e32 v23, v7, v23
	global_store_dwordx4 v80, v[20:23], s[0:1] offset:1024 nt
	v_mul_f32_e32 v24, v24, v68
	v_mul_f32_e32 v25, v25, v68
	v_mul_f32_e32 v26, v26, v68
	v_mul_f32_e32 v27, v27, v68
	v_mul_f32_e32 v24, v8, v24
	v_mul_f32_e32 v25, v9, v25
	v_mul_f32_e32 v26, v10, v26
	v_mul_f32_e32 v27, v11, v27
	global_store_dwordx4 v80, v[24:27], s[0:1] offset:2048 nt
	v_mul_f32_e32 v28, v28, v68
	v_mul_f32_e32 v29, v29, v68
	v_mul_f32_e32 v30, v30, v68
	v_mul_f32_e32 v31, v31, v68
	v_mul_f32_e32 v28, v12, v28
	v_mul_f32_e32 v29, v13, v29
	v_mul_f32_e32 v30, v14, v30
	v_mul_f32_e32 v31, v15, v31
	global_store_dwordx4 v80, v[28:31], s[0:1] offset:3072 nt
	s_add_i32 s11, s11, s84
	s_cmp_ge_u32 s11, 0x10100
	s_cbranch_scc1 .LBB0_806
	s_lshl_b32 s20, s84, 1
	s_add_i32 s20, s11, s20
	s_cmp_lt_u32 s20, 0x10100
	s_cselect_b32 s20, s20, s11
	s_mov_b32 s16, s20
	s_lshl_b32 s17, s16, 11
	s_add_u32 s14, s4, s17
	s_addc_u32 s15, s5, 0
	s_add_i32 s18, s16, 0xffff0000
	s_cmp_lt_u32 s16, 0x10000
	s_cselect_b32 s18, s16, s18
	s_cselect_b32 s12, s68, s70
	s_cselect_b32 s13, s69, s71
	s_lshr_b32 s19, s18, 20
	s_lshl_b32 s18, s18, 12
	s_add_u32 s12, s12, s18
	s_addc_u32 s13, s13, s19
	global_load_dwordx4 v[16:19], v80, s[12:13] nt
	global_load_dwordx4 v[20:23], v80, s[12:13] offset:1024 nt
	global_load_dwordx4 v[24:27], v80, s[12:13] offset:2048 nt
	global_load_dwordx4 v[28:31], v80, s[12:13] offset:3072 nt
	global_load_dwordx2 v[32:33], v81, s[14:15]
	global_load_dwordx2 v[34:35], v81, s[14:15] offset:512
	global_load_dwordx2 v[36:37], v81, s[14:15] offset:1024
	global_load_dwordx2 v[38:39], v81, s[14:15] offset:1536
	s_lshr_b32 s19, s11, 20
	s_lshl_b32 s18, s11, 12
	s_add_u32 s0, s90, s18
	s_addc_u32 s1, s91, s19
	s_waitcnt vmcnt(16)
	v_lshlrev_b32_e32 v64, 16, v56
	v_and_b32_e32 v65, 0xffff0000, v56
	v_add_f32_e32 v40, v40, v64
	v_add_f32_e32 v41, v41, v65
	v_lshlrev_b32_e32 v64, 16, v57
	v_and_b32_e32 v65, 0xffff0000, v57
	v_add_f32_e32 v42, v42, v64
	v_add_f32_e32 v43, v43, v65
	v_lshlrev_b32_e32 v64, 16, v58
	v_and_b32_e32 v65, 0xffff0000, v58
	v_add_f32_e32 v44, v44, v64
	v_add_f32_e32 v45, v45, v65
	v_lshlrev_b32_e32 v64, 16, v59
	v_and_b32_e32 v65, 0xffff0000, v59
	v_add_f32_e32 v46, v46, v64
	v_add_f32_e32 v47, v47, v65
	v_lshlrev_b32_e32 v64, 16, v60
	v_and_b32_e32 v65, 0xffff0000, v60
	v_add_f32_e32 v48, v48, v64
	v_add_f32_e32 v49, v49, v65
	v_lshlrev_b32_e32 v64, 16, v61
	v_and_b32_e32 v65, 0xffff0000, v61
	v_add_f32_e32 v50, v50, v64
	v_add_f32_e32 v51, v51, v65
	v_lshlrev_b32_e32 v64, 16, v62
	v_and_b32_e32 v65, 0xffff0000, v62
	v_add_f32_e32 v52, v52, v64
	v_add_f32_e32 v53, v53, v65
	v_lshlrev_b32_e32 v64, 16, v63
	v_and_b32_e32 v65, 0xffff0000, v63
	v_add_f32_e32 v54, v54, v64
	v_add_f32_e32 v55, v55, v65
	v_mul_f32_e32 v64, v40, v40
	v_mul_f32_e32 v65, v41, v41
	v_mul_f32_e32 v66, v42, v42
	v_mul_f32_e32 v67, v43, v43
	v_add_f32_e32 v64, v64, v65
	v_add_f32_e32 v66, v66, v67
	v_add_f32_e32 v68, v64, v66
	v_mul_f32_e32 v64, v44, v44
	v_mul_f32_e32 v65, v45, v45
	v_mul_f32_e32 v66, v46, v46
	v_mul_f32_e32 v67, v47, v47
	v_add_f32_e32 v64, v64, v65
	v_add_f32_e32 v66, v66, v67
	v_add_f32_e32 v64, v64, v66
	v_add_f32_e32 v68, v68, v64
	v_mul_f32_e32 v64, v48, v48
	v_mul_f32_e32 v65, v49, v49
	v_mul_f32_e32 v66, v50, v50
	v_mul_f32_e32 v67, v51, v51
	v_add_f32_e32 v64, v64, v65
	v_add_f32_e32 v66, v66, v67
	v_add_f32_e32 v64, v64, v66
	v_add_f32_e32 v68, v68, v64
	v_mul_f32_e32 v64, v52, v52
	v_mul_f32_e32 v65, v53, v53
	v_mul_f32_e32 v66, v54, v54
	v_mul_f32_e32 v67, v55, v55
	v_add_f32_e32 v64, v64, v65
	v_add_f32_e32 v66, v66, v67
	v_add_f32_e32 v64, v64, v66
	v_add_f32_e32 v68, v68, v64
	ds_bpermute_b32 v69, v72, v68
	s_waitcnt lgkmcnt(0)
; __device__ __forceinline__ void phase4(const Params& P, int lane, int wave) {
;     ...
;         ss = wave_sum(ss);
;         const float rstd = 1.0f / sqrtf(ss * (1.0f / 1024.0f) + RMS_EPS);
;         float* row = P.out + (size_t)m * 1024;
; #pragma unroll
;         for (int j = 0; j < 4; ++j) *(f32x4*)(row + 4 * lane + 256 * j) = r[j] * rstd * g4[j];
	v_add_f32_e32 v68, v68, v69
	ds_bpermute_b32 v69, v73, v68
	s_waitcnt lgkmcnt(0)
	v_add_f32_e32 v68, v68, v69
	ds_bpermute_b32 v69, v74, v68
	s_waitcnt lgkmcnt(0)
	v_add_f32_e32 v68, v68, v69
	ds_bpermute_b32 v69, v75, v68
	s_waitcnt lgkmcnt(0)
	v_add_f32_e32 v68, v68, v69
	ds_bpermute_b32 v69, v76, v68
	s_waitcnt lgkmcnt(0)
	v_add_f32_e32 v68, v68, v69
	ds_bpermute_b32 v69, v77, v68
	s_waitcnt lgkmcnt(0)
	v_add_f32_e32 v68, v68, v69
	v_fmamk_f32 v68, v68, 0x3a800000, v70
	v_mul_f32_e32 v69, 0x4f800000, v68
	v_cmp_gt_f32_e32 vcc, s2, v68
	s_nop 1
	v_cndmask_b32_e32 v68, v68, v69, vcc
	v_sqrt_f32_e32 v69, v68
	s_nop 0
	v_add_u32_e32 v64, -1, v69
	v_fma_f32 v65, -v64, v69, v68
	v_cmp_ge_f32_e64 s[6:7], 0, v65
	v_add_u32_e32 v65, 1, v69
	s_nop 0
	v_cndmask_b32_e64 v64, v69, v64, s[6:7]
	v_fma_f32 v69, -v65, v69, v68
	v_cmp_lt_f32_e64 s[6:7], 0, v69
	s_nop 1
	v_cndmask_b32_e64 v69, v64, v65, s[6:7]
	v_mul_f32_e32 v64, 0x37800000, v69
	v_cndmask_b32_e32 v69, v69, v64, vcc
	v_cmp_class_f32_e32 vcc, v68, v71
	s_nop 1
	v_cndmask_b32_e32 v68, v69, v68, vcc
	v_div_scale_f32 v69, s[6:7], v68, v68, 1.0
	v_rcp_f32_e32 v64, v69
	s_nop 0
	v_fma_f32 v65, -v69, v64, 1.0
	v_fmac_f32_e32 v64, v65, v64
	v_div_scale_f32 v65, vcc, 1.0, v68, 1.0
	v_mul_f32_e32 v66, v65, v64
	v_fma_f32 v67, -v69, v66, v65
	v_fmac_f32_e32 v66, v67, v64
	v_fma_f32 v69, -v69, v66, v65
	v_div_fmas_f32 v69, v69, v64, v66
	v_div_fixup_f32 v68, v69, v68, 1.0
	v_mul_f32_e32 v40, v40, v68
	v_mul_f32_e32 v41, v41, v68
	v_mul_f32_e32 v42, v42, v68
	v_mul_f32_e32 v43, v43, v68
	v_mul_f32_e32 v40, v0, v40
	v_mul_f32_e32 v41, v1, v41
	v_mul_f32_e32 v42, v2, v42
	v_mul_f32_e32 v43, v3, v43
	global_store_dwordx4 v80, v[40:43], s[0:1] nt
	v_mul_f32_e32 v44, v44, v68
	v_mul_f32_e32 v45, v45, v68
	v_mul_f32_e32 v46, v46, v68
	v_mul_f32_e32 v47, v47, v68
	v_mul_f32_e32 v44, v4, v44
	v_mul_f32_e32 v45, v5, v45
	v_mul_f32_e32 v46, v6, v46
	v_mul_f32_e32 v47, v7, v47
	global_store_dwordx4 v80, v[44:47], s[0:1] offset:1024 nt
	v_mul_f32_e32 v48, v48, v68
	v_mul_f32_e32 v49, v49, v68
	v_mul_f32_e32 v50, v50, v68
	v_mul_f32_e32 v51, v51, v68
	v_mul_f32_e32 v48, v8, v48
	v_mul_f32_e32 v49, v9, v49
	v_mul_f32_e32 v50, v10, v50
	v_mul_f32_e32 v51, v11, v51
	global_store_dwordx4 v80, v[48:51], s[0:1] offset:2048 nt
	v_mul_f32_e32 v52, v52, v68
	v_mul_f32_e32 v53, v53, v68
	v_mul_f32_e32 v54, v54, v68
	v_mul_f32_e32 v55, v55, v68
	v_mul_f32_e32 v52, v12, v52
	v_mul_f32_e32 v53, v13, v53
	v_mul_f32_e32 v54, v14, v54
	v_mul_f32_e32 v55, v15, v55
	global_store_dwordx4 v80, v[52:55], s[0:1] offset:3072 nt
	s_add_i32 s11, s11, s84
	s_cmp_ge_u32 s11, 0x10100
	s_cbranch_scc1 .LBB0_806
; __device__ __forceinline__ float bf_lo(unsigned w) { return __uint_as_float(w << 16); }
; __device__ __forceinline__ float bf_hi(unsigned w) { return __uint_as_float(w & 0xffff0000u); }
; __device__ __forceinline__ void phase4(const Params& P, int lane, int wave) {
;     ...
;         for (int j = 0; j < 4; ++j) {
;             r[j][0] = v[j][0] + bf_lo(mv[j].x); r[j][1] = v[j][1] + bf_hi(mv[j].x); r[j][2] = v[j][2] + bf_lo(mv[j].y); r[j][3] = v[j][3] + bf_hi(mv[j].y);
;             ss += (r[j][0] * r[j][0] + r[j][1] * r[j][1]) + (r[j][2] * r[j][2] + r[j][3] * r[j][3]);
;         }
;         const int mn = m + NGW;
;         if (mn < MT) {
;             const float* xrow = (mn < MP) ? P.xp + (size_t)mn * 1024 : P.xs + (size_t)(mn - MP) * 1024;
; #pragma unroll
;             for (int j = 0; j < 4; ++j) { v[j] = *(const f32x4*)(xrow + 4 * lane + 256 * j); mv[j] = *(const u32x2*)(mo + (size_t)mn * 1024 + 4 * lane + 256 * j); }
;         }
;         ss = wave_sum(ss);
;         const float rstd = 1.0f / sqrtf(ss * (1.0f / 1024.0f) + RMS_EPS);
;         float* row = P.out + (size_t)m * 1024;
; #pragma unroll
;         for (int j = 0; j < 4; ++j) *(f32x4*)(row + 4 * lane + 256 * j) = r[j] * rstd * g4[j];
	s_lshl_b32 s20, s84, 1
	s_add_i32 s20, s11, s20
	s_cmp_lt_u32 s20, 0x10100
	s_cselect_b32 s20, s20, s11
	s_mov_b32 s16, s20
	s_lshl_b32 s17, s16, 11
	s_add_u32 s14, s4, s17
	s_addc_u32 s15, s5, 0
	s_add_i32 s18, s16, 0xffff0000
	s_cmp_lt_u32 s16, 0x10000
	s_cselect_b32 s18, s16, s18
	s_cselect_b32 s12, s68, s70
	s_cselect_b32 s13, s69, s71
	s_lshr_b32 s19, s18, 20
	s_lshl_b32 s18, s18, 12
	s_add_u32 s12, s12, s18
	s_addc_u32 s13, s13, s19
	global_load_dwordx4 v[40:43], v80, s[12:13] nt
	global_load_dwordx4 v[44:47], v80, s[12:13] offset:1024 nt
	global_load_dwordx4 v[48:51], v80, s[12:13] offset:2048 nt
	global_load_dwordx4 v[52:55], v80, s[12:13] offset:3072 nt
	global_load_dwordx2 v[56:57], v81, s[14:15]
	global_load_dwordx2 v[58:59], v81, s[14:15] offset:512
	global_load_dwordx2 v[60:61], v81, s[14:15] offset:1024
	global_load_dwordx2 v[62:63], v81, s[14:15] offset:1536
	s_lshr_b32 s19, s11, 20
	s_lshl_b32 s18, s11, 12
	s_add_u32 s0, s90, s18
	s_addc_u32 s1, s91, s19
	s_waitcnt vmcnt(16)
	v_lshlrev_b32_e32 v64, 16, v104
	v_and_b32_e32 v65, 0xffff0000, v104
	v_add_f32_e32 v88, v88, v64
	v_add_f32_e32 v89, v89, v65
	v_lshlrev_b32_e32 v64, 16, v105
	v_and_b32_e32 v65, 0xffff0000, v105
	v_add_f32_e32 v90, v90, v64
	v_add_f32_e32 v91, v91, v65
	v_lshlrev_b32_e32 v64, 16, v106
	v_and_b32_e32 v65, 0xffff0000, v106
	v_add_f32_e32 v92, v92, v64
	v_add_f32_e32 v93, v93, v65
	v_lshlrev_b32_e32 v64, 16, v107
	v_and_b32_e32 v65, 0xffff0000, v107
	v_add_f32_e32 v94, v94, v64
	v_add_f32_e32 v95, v95, v65
	v_lshlrev_b32_e32 v64, 16, v108
	v_and_b32_e32 v65, 0xffff0000, v108
	v_add_f32_e32 v96, v96, v64
	v_add_f32_e32 v97, v97, v65
	v_lshlrev_b32_e32 v64, 16, v109
	v_and_b32_e32 v65, 0xffff0000, v109
	v_add_f32_e32 v98, v98, v64
	v_add_f32_e32 v99, v99, v65
	v_lshlrev_b32_e32 v64, 16, v110
	v_and_b32_e32 v65, 0xffff0000, v110
	v_add_f32_e32 v100, v100, v64
	v_add_f32_e32 v101, v101, v65
	v_lshlrev_b32_e32 v64, 16, v111
	v_and_b32_e32 v65, 0xffff0000, v111
	v_add_f32_e32 v102, v102, v64
	v_add_f32_e32 v103, v103, v65
	v_mul_f32_e32 v64, v88, v88
	v_mul_f32_e32 v65, v89, v89
	v_mul_f32_e32 v66, v90, v90
	v_mul_f32_e32 v67, v91, v91
	v_add_f32_e32 v64, v64, v65
	v_add_f32_e32 v66, v66, v67
	v_add_f32_e32 v68, v64, v66
	v_mul_f32_e32 v64, v92, v92
	v_mul_f32_e32 v65, v93, v93
	v_mul_f32_e32 v66, v94, v94
	v_mul_f32_e32 v67, v95, v95
	v_add_f32_e32 v64, v64, v65
	v_add_f32_e32 v66, v66, v67
	v_add_f32_e32 v64, v64, v66
	v_add_f32_e32 v68, v68, v64
	v_mul_f32_e32 v64, v96, v96
	v_mul_f32_e32 v65, v97, v97
	v_mul_f32_e32 v66, v98, v98
	v_mul_f32_e32 v67, v99, v99
	v_add_f32_e32 v64, v64, v65
	v_add_f32_e32 v66, v66, v67
	v_add_f32_e32 v64, v64, v66
	v_add_f32_e32 v68, v68, v64
	v_mul_f32_e32 v64, v100, v100
	v_mul_f32_e32 v65, v101, v101
	v_mul_f32_e32 v66, v102, v102
	v_mul_f32_e32 v67, v103, v103
	v_add_f32_e32 v64, v64, v65
	v_add_f32_e32 v66, v66, v67
	v_add_f32_e32 v64, v64, v66
	v_add_f32_e32 v68, v68, v64
	ds_bpermute_b32 v69, v72, v68
	s_waitcnt lgkmcnt(0)
	v_add_f32_e32 v68, v68, v69
	ds_bpermute_b32 v69, v73, v68
	s_waitcnt lgkmcnt(0)
	v_add_f32_e32 v68, v68, v69
	ds_bpermute_b32 v69, v74, v68
	s_waitcnt lgkmcnt(0)
	v_add_f32_e32 v68, v68, v69
	ds_bpermute_b32 v69, v75, v68
	s_waitcnt lgkmcnt(0)
	v_add_f32_e32 v68, v68, v69
	ds_bpermute_b32 v69, v76, v68
	s_waitcnt lgkmcnt(0)
	v_add_f32_e32 v68, v68, v69
	ds_bpermute_b32 v69, v77, v68
	s_waitcnt lgkmcnt(0)
	v_add_f32_e32 v68, v68, v69
	v_fmamk_f32 v68, v68, 0x3a800000, v70
	v_mul_f32_e32 v69, 0x4f800000, v68
	v_cmp_gt_f32_e32 vcc, s2, v68
	s_nop 1
	v_cndmask_b32_e32 v68, v68, v69, vcc
	v_sqrt_f32_e32 v69, v68
	s_nop 0
	v_add_u32_e32 v64, -1, v69
	v_fma_f32 v65, -v64, v69, v68
	v_cmp_ge_f32_e64 s[6:7], 0, v65
	v_add_u32_e32 v65, 1, v69
	s_nop 0
	v_cndmask_b32_e64 v64, v69, v64, s[6:7]
	v_fma_f32 v69, -v65, v69, v68
	v_cmp_lt_f32_e64 s[6:7], 0, v69
	s_nop 1
	v_cndmask_b32_e64 v69, v64, v65, s[6:7]
	v_mul_f32_e32 v64, 0x37800000, v69
	v_cndmask_b32_e32 v69, v69, v64, vcc
	v_cmp_class_f32_e32 vcc, v68, v71
	s_nop 1
	v_cndmask_b32_e32 v68, v69, v68, vcc
	v_div_scale_f32 v69, s[6:7], v68, v68, 1.0
	v_rcp_f32_e32 v64, v69
	s_nop 0
	v_fma_f32 v65, -v69, v64, 1.0
	v_fmac_f32_e32 v64, v65, v64
	v_div_scale_f32 v65, vcc, 1.0, v68, 1.0
	v_mul_f32_e32 v66, v65, v64
	v_fma_f32 v67, -v69, v66, v65
	v_fmac_f32_e32 v66, v67, v64
	v_fma_f32 v69, -v69, v66, v65
	v_div_fmas_f32 v69, v69, v64, v66
	v_div_fixup_f32 v68, v69, v68, 1.0
	v_mul_f32_e32 v88, v88, v68
	v_mul_f32_e32 v89, v89, v68
	v_mul_f32_e32 v90, v90, v68
	v_mul_f32_e32 v91, v91, v68
	v_mul_f32_e32 v88, v0, v88
	v_mul_f32_e32 v89, v1, v89
	v_mul_f32_e32 v90, v2, v90
	v_mul_f32_e32 v91, v3, v91
	global_store_dwordx4 v80, v[88:91], s[0:1] nt
	v_mul_f32_e32 v92, v92, v68
	v_mul_f32_e32 v93, v93, v68
	v_mul_f32_e32 v94, v94, v68
	v_mul_f32_e32 v95, v95, v68
	v_mul_f32_e32 v92, v4, v92
	v_mul_f32_e32 v93, v5, v93
	v_mul_f32_e32 v94, v6, v94
	v_mul_f32_e32 v95, v7, v95
	global_store_dwordx4 v80, v[92:95], s[0:1] offset:1024 nt
	v_mul_f32_e32 v96, v96, v68
	v_mul_f32_e32 v97, v97, v68
	v_mul_f32_e32 v98, v98, v68
	v_mul_f32_e32 v99, v99, v68
	v_mul_f32_e32 v96, v8, v96
	v_mul_f32_e32 v97, v9, v97
	v_mul_f32_e32 v98, v10, v98
	v_mul_f32_e32 v99, v11, v99
	global_store_dwordx4 v80, v[96:99], s[0:1] offset:2048 nt
	v_mul_f32_e32 v100, v100, v68
	v_mul_f32_e32 v101, v101, v68
	v_mul_f32_e32 v102, v102, v68
	v_mul_f32_e32 v103, v103, v68
	v_mul_f32_e32 v100, v12, v100
	v_mul_f32_e32 v101, v13, v101
	v_mul_f32_e32 v102, v14, v102
	v_mul_f32_e32 v103, v15, v103
	global_store_dwordx4 v80, v[100:103], s[0:1] offset:3072 nt
	s_add_i32 s11, s11, s84
	s_cmp_ge_u32 s11, 0x10100
	s_cbranch_scc1 .LBB0_806
	s_branch .Lp4_loop
